# adds software prefetch of the next row and hoisted gain loads to both final rms-norm loops, on top of the lean unrolled dil loop
# speedup vs baseline: 1.0139x; 1.0139x over previous
; #define GAS __attribute__((address_space(1)))
; template <bool FIRST>
; __device__ __forceinline__ void norm_phase(const float* xp, const float* xs, float* out, unsigned char* ws, int mode, const float* gain, int gw, int NGW, int lane) {
;     asm volatile("" : "+v"(lane));
;     bf16_t* xb = (bf16_t*)(ws + WS_XB);
;     float* ss1 = (float*)(ws + WS_SS1);
;     for (int m = gw; m < M; m += NGW) {
;         f32x4 v[4]; float s = 0.f;
;         if (FIRST) {
;             const float* src = (m < SEQ ? xp + (size_t)m * D : xs + (size_t)(m - SEQ) * D);
; #pragma unroll
;             for (int j = 0; j < 4; ++j) v[j] = *((const GAS f32x4*)src + lane + 64 * j);
;         } else {
; #pragma unroll
;             for (int j = 0; j < 4; ++j) { const u32x2 w = *((const GAS u32x2*)(xb + (size_t)m * D) + lane + 64 * j);
;                 v[j] = (f32x4){__uint_as_float(w.x << 16), __uint_as_float(w.x & 0xffff0000u), __uint_as_float(w.y << 16), __uint_as_float(w.y & 0xffff0000u)}; }
;         }
; #pragma unroll
;         for (int j = 0; j < 4; ++j) s += (v[j][0] * v[j][0] + v[j][1] * v[j][1]) + (v[j][2] * v[j][2] + v[j][3] * v[j][3]);
;         s = wave_sum(s);
;         if (!FIRST) {
;             const float rs = __builtin_amdgcn_rsqf(s * (1.0f / 1024.0f) + EPS); float s2 = 0.f;
; #pragma unroll
;             for (int j = 0; j < 4; ++j) { const f32x4 gg = *((const GAS f32x4*)gain + lane + 64 * j); v[j] = v[j] * rs * gg; s2 += (v[j][0] * v[j][0] + v[j][1] * v[j][1]) + (v[j][2] * v[j][2] + v[j][3] * v[j][3]); }
.LBB0_818:
	s_or_b64 exec, exec, s[46:47]
	v_cndmask_b32_e64 v1, 0, 1, s[40:41]
	s_mov_b64 s[12:13], s[42:43]
	v_mov_b32_e32 v0, v152
	v_cmp_ne_u32_e64 s[6:7], 1, v1
	s_andn2_b64 vcc, exec, s[40:41]
	s_waitcnt lgkmcnt(0)
	s_barrier
	s_cbranch_vccnz .LBB0_823
	v_mbcnt_hi_u32_b32 v2, -1, v155
	v_and_b32_e32 v3, 64, v2
	v_add_u32_e32 v3, 64, v3
	v_xor_b32_e32 v4, 1, v2
	v_cmp_lt_i32_e32 vcc, v4, v3
	v_ashrrev_i32_e32 v1, 31, v0
	s_mov_b64 s[8:9], 0xc3000
	v_cndmask_b32_e32 v4, v2, v4, vcc
	v_lshlrev_b32_e32 v6, 2, v4
	v_xor_b32_e32 v4, 2, v2
	v_cmp_lt_i32_e32 vcc, v4, v3
	s_ashr_i32 s69, s68, 31
	v_mov_b32_e32 v12, 0x358637bd
	v_cndmask_b32_e32 v4, v2, v4, vcc
	v_lshlrev_b32_e32 v7, 2, v4
	v_xor_b32_e32 v4, 4, v2
	v_cmp_lt_i32_e32 vcc, v4, v3
	s_mov_b32 s15, s68
	s_nop 0
	v_cndmask_b32_e32 v4, v2, v4, vcc
	v_lshlrev_b32_e32 v8, 2, v4
	v_xor_b32_e32 v4, 8, v2
	v_cmp_lt_i32_e32 vcc, v4, v3
	s_nop 1
	v_cndmask_b32_e32 v4, v2, v4, vcc
	v_lshlrev_b32_e32 v9, 2, v4
	v_xor_b32_e32 v4, 16, v2
	v_cmp_lt_i32_e32 vcc, v4, v3
	s_nop 1
	v_cndmask_b32_e32 v4, v2, v4, vcc
	v_lshlrev_b32_e32 v10, 2, v4
	v_xor_b32_e32 v4, 32, v2
	v_cmp_lt_i32_e32 vcc, v4, v3
	s_nop 1
	v_cndmask_b32_e32 v2, v2, v4, vcc
	v_lshlrev_b32_e32 v11, 2, v2
	v_lshl_add_u64 v[2:3], v[0:1], 4, s[12:13]
	v_lshl_add_u64 v[2:3], v[2:3], 0, s[8:9]
	s_lshl_b64 s[8:9], s[68:69], 2
	s_add_u32 s8, s12, s8
	s_addc_u32 s9, s13, s9
	s_ashr_i32 s71, s70, 31
	s_lshl_b64 s[10:11], s[70:71], 2
	s_lshl_b64 s[16:17], s[68:69], 11
	s_add_u32 s12, s12, s16
	s_addc_u32 s13, s13, s17
	s_add_u32 s12, s12, 0x5400000
	v_cmp_eq_u32_e32 vcc, 0, v0
	s_addc_u32 s13, s13, 0
	s_lshl_b64 s[16:17], s[70:71], 11
	global_load_dwordx4 v[160:163], v[2:3], off
	global_load_dwordx4 v[164:167], v[2:3], off offset:1024
	global_load_dwordx4 v[168:171], v[2:3], off offset:2048
	global_load_dwordx4 v[172:175], v[2:3], off offset:3072
	v_lshl_add_u64 v[84:85], v[0:1], 3, s[12:13]
	global_load_dwordx2 v[76:77], v[84:85], off offset:1536
	global_load_dwordx2 v[78:79], v[84:85], off
	global_load_dwordx2 v[80:81], v[84:85], off offset:512
	global_load_dwordx2 v[82:83], v[84:85], off offset:1024
	s_waitcnt vmcnt(0)
	s_branch .LBB0_821

; #define GAS __attribute__((address_space(1)))
; __device__ __forceinline__ unsigned cvt_pk_bf16(float lo, float hi) { f32x2_t v = {lo, hi}; bf16x2_t b = __builtin_convertvector(v, bf16x2_t); return __builtin_bit_cast(unsigned, b); }
; template <bool FIRST>
; __device__ __forceinline__ void norm_phase(const float* xp, const float* xs, float* out, unsigned char* ws, int mode, const float* gain, int gw, int NGW, int lane) {
;     ...
;     for (int m = gw; m < M; m += NGW) {
;         f32x4 v[4]; float s = 0.f;
;         if (FIRST) {
;             const float* src = (m < SEQ ? xp + (size_t)m * D : xs + (size_t)(m - SEQ) * D);
; #pragma unroll
;             for (int j = 0; j < 4; ++j) v[j] = *((const GAS f32x4*)src + lane + 64 * j);
;         } else {
; #pragma unroll
;             for (int j = 0; j < 4; ++j) { const u32x2 w = *((const GAS u32x2*)(xb + (size_t)m * D) + lane + 64 * j);
;                 v[j] = (f32x4){__uint_as_float(w.x << 16), __uint_as_float(w.x & 0xffff0000u), __uint_as_float(w.y << 16), __uint_as_float(w.y & 0xffff0000u)}; }
;         }
; #pragma unroll
;         for (int j = 0; j < 4; ++j) s += (v[j][0] * v[j][0] + v[j][1] * v[j][1]) + (v[j][2] * v[j][2] + v[j][3] * v[j][3]);
;         s = wave_sum(s);
;         if (!FIRST) {
;             const float rs = __builtin_amdgcn_rsqf(s * (1.0f / 1024.0f) + EPS); float s2 = 0.f;
; #pragma unroll
;             for (int j = 0; j < 4; ++j) { const f32x4 gg = *((const GAS f32x4*)gain + lane + 64 * j); v[j] = v[j] * rs * gg; s2 += (v[j][0] * v[j][0] + v[j][1] * v[j][1]) + (v[j][2] * v[j][2] + v[j][3] * v[j][3]); }
;             s = wave_sum(s2);
;         }
;         if (mode == 2) {
; #pragma unroll
;             for (int j = 0; j < 4; ++j) *((GAS f32x4*)(out + (size_t)m * D) + lane + 64 * j) = v[j];
;         } else {
; #pragma unroll
;             for (int j = 0; j < 4; ++j) { u32x2 w; w.x = cvt_pk_bf16(v[j][0], v[j][1]); w.y = cvt_pk_bf16(v[j][2], v[j][3]); *((GAS u32x2*)(xb + (size_t)m * D) + lane + 64 * j) = w; }
;             if (lane == 0) ss1[m] = s;
;         }
.LBB0_821:
	v_lshl_add_u64 v[4:5], v[0:1], 3, s[12:13]
	s_add_u32 s98, s12, s16
	s_addc_u32 s99, s13, s17
	s_waitcnt vmcnt(4) lgkmcnt(0)
	v_mov_b64_e32 v[30:31], v[76:77]
	v_mov_b64_e32 v[32:33], v[78:79]
	v_mov_b64_e32 v[34:35], v[80:81]
	v_mov_b64_e32 v[36:37], v[82:83]
	v_lshl_add_u64 v[84:85], v[0:1], 3, s[98:99]
	global_load_dwordx2 v[76:77], v[84:85], off offset:1536
	global_load_dwordx2 v[78:79], v[84:85], off
	global_load_dwordx2 v[80:81], v[84:85], off offset:512
	global_load_dwordx2 v[82:83], v[84:85], off offset:1024
	v_lshlrev_b32_e32 v39, 16, v30
	v_lshlrev_b32_e32 v42, 16, v32
	v_and_b32_e32 v43, 0xffff0000, v32
	v_lshlrev_b32_e32 v32, 16, v33
	v_and_b32_e32 v33, 0xffff0000, v33
	v_and_b32_e32 v41, 0xffff0000, v30
	v_lshlrev_b32_e32 v45, 16, v35
	v_lshlrev_b32_e32 v44, 16, v34
	v_and_b32_e32 v35, 0xffff0000, v35
	v_and_b32_e32 v34, 0xffff0000, v34
	v_and_b32_e32 v47, 0xffff0000, v36
	v_mul_f32_e32 v38, v33, v33
	v_mul_f32_e32 v40, v43, v43
	v_lshlrev_b32_e32 v46, 16, v36
	v_lshlrev_b32_e32 v36, 16, v37
	v_and_b32_e32 v37, 0xffff0000, v37
	v_pk_mul_f32 v[48:49], v[34:35], v[34:35]
	v_mov_b32_e32 v51, v39
	v_mul_f32_e32 v50, v47, v47
	v_pk_fma_f32 v[54:55], v[32:33], v[32:33], v[38:39] op_sel_hi:[1,1,0]
	v_pk_fma_f32 v[56:57], v[42:43], v[42:43], v[40:41] op_sel_hi:[1,1,0]
	v_lshlrev_b32_e32 v30, 16, v31
	v_and_b32_e32 v31, 0xffff0000, v31
	v_mul_f32_e32 v52, v37, v37
	v_pk_fma_f32 v[48:49], v[44:45], v[44:45], v[48:49]
	v_pk_fma_f32 v[58:59], v[46:47], v[46:47], v[50:51] op_sel_hi:[1,1,0]
	v_mov_b32_e32 v38, v56
	v_mov_b32_e32 v50, v54
	v_mul_f32_e32 v13, v41, v41
	v_mul_f32_e32 v60, v30, v30
	v_mul_f32_e32 v61, v31, v31
	v_pk_fma_f32 v[52:53], v[36:37], v[36:37], v[52:53] op_sel_hi:[1,1,0]
	v_pk_add_f32 v[54:55], v[56:57], v[54:55]
	v_pk_add_f32 v[48:49], v[48:49], v[48:49] op_sel:[0,1] op_sel_hi:[1,0]
	v_pk_mul_f32 v[50:51], v[38:39], v[50:51]
	v_mov_b32_e32 v59, v60
	v_mov_b32_e32 v53, v61
	v_mov_b32_e32 v49, v13
	v_mov_b32_e32 v55, v51
	v_pk_add_f32 v[52:53], v[58:59], v[52:53]
	v_pk_add_f32 v[48:49], v[54:55], v[48:49]
	v_mov_b32_e32 v40, v39
	v_pk_add_f32 v[48:49], v[48:49], v[52:53]
	s_nop 0
	v_add_f32_e32 v13, v48, v49
	ds_bpermute_b32 v38, v6, v13
	v_mov_b32_e32 v48, v44
	v_mov_b32_e32 v49, v34
	v_mov_b32_e32 v34, v45
	s_waitcnt lgkmcnt(0)
	v_add_f32_e32 v13, v13, v38
	ds_bpermute_b32 v38, v7, v13
	s_waitcnt lgkmcnt(0)
	v_add_f32_e32 v13, v13, v38
	ds_bpermute_b32 v38, v8, v13
	s_waitcnt lgkmcnt(0)
	v_add_f32_e32 v13, v13, v38
	ds_bpermute_b32 v38, v9, v13
	s_waitcnt lgkmcnt(0)
	v_add_f32_e32 v13, v13, v38
	ds_bpermute_b32 v38, v10, v13
	s_waitcnt lgkmcnt(0)
	v_add_f32_e32 v13, v13, v38
	ds_bpermute_b32 v38, v11, v13
	s_waitcnt lgkmcnt(0)
	v_add_f32_e32 v13, v13, v38
	v_fmamk_f32 v13, v13, 0x3a800000, v12
	v_rsq_f32_e32 v38, v13
	s_nop 0
	v_pk_mul_f32 v[42:43], v[38:39], v[42:43] op_sel_hi:[0,1]
	v_pk_mul_f32 v[32:33], v[38:39], v[32:33] op_sel_hi:[0,1]
	v_pk_mul_f32 v[44:45], v[38:39], v[48:49] op_sel_hi:[0,1]
	v_pk_mul_f32 v[34:35], v[38:39], v[34:35] op_sel_hi:[0,1]
	v_pk_mul_f32 v[46:47], v[38:39], v[46:47] op_sel_hi:[0,1]
	v_pk_mul_f32 v[36:37], v[38:39], v[36:37] op_sel_hi:[0,1]
	v_pk_mul_f32 v[30:31], v[30:31], v[38:39] op_sel_hi:[1,0]
	v_pk_mul_f32 v[16:17], v[162:163], v[32:33]
	v_pk_mul_f32 v[14:15], v[160:161], v[42:43]
	v_pk_mul_f32 v[20:21], v[166:167], v[34:35]
	v_pk_mul_f32 v[18:19], v[164:165], v[44:45]
	v_pk_mul_f32 v[40:41], v[40:41], v[38:39] op_sel_hi:[1,0]
	v_pk_mul_f32 v[24:25], v[170:171], v[36:37]
	v_pk_mul_f32 v[22:23], v[168:169], v[46:47]
	v_pk_mul_f32 v[28:29], v[174:175], v[30:31]
	v_mul_f32_e32 v13, v15, v15
	v_mul_f32_e32 v30, v17, v17
	v_mul_f32_e32 v31, v19, v19
	v_mul_f32_e32 v32, v21, v21
	v_pk_mul_f32 v[26:27], v[172:173], v[40:41]
	v_mul_f32_e32 v33, v23, v23
	v_mul_f32_e32 v34, v25, v25
	v_fmac_f32_e32 v13, v14, v14
	v_fmac_f32_e32 v30, v16, v16
	v_fmac_f32_e32 v31, v18, v18
	v_fmac_f32_e32 v32, v20, v20
	v_mul_f32_e32 v35, v27, v27
	v_mul_f32_e32 v36, v29, v29
	v_fmac_f32_e32 v33, v22, v22
	v_fmac_f32_e32 v34, v24, v24
	v_add_f32_e32 v13, v13, v30
	v_add_f32_e32 v30, v31, v32
	v_fmac_f32_e32 v35, v26, v26
	v_fmac_f32_e32 v36, v28, v28
	v_add_f32_e32 v31, v33, v34
	v_add_f32_e32 v13, v13, v30
	v_add_f32_e32 v32, v35, v36
	v_add_f32_e32 v13, v31, v13
	v_add_f32_e32 v13, v32, v13
	ds_bpermute_b32 v30, v6, v13
	v_cvt_pk_bf16_f32 v14, v14, v15
	v_cvt_pk_bf16_f32 v15, v16, v17
	v_cvt_pk_bf16_f32 v16, v18, v19
	v_cvt_pk_bf16_f32 v17, v20, v21
	s_waitcnt lgkmcnt(0)
	v_add_f32_e32 v13, v13, v30
	ds_bpermute_b32 v30, v7, v13
	global_store_dwordx2 v[4:5], v[14:15], off
	global_store_dwordx2 v[4:5], v[16:17], off offset:512
	v_cvt_pk_bf16_f32 v18, v22, v23
	v_cvt_pk_bf16_f32 v16, v26, v27
	v_cvt_pk_bf16_f32 v17, v28, v29
	s_waitcnt lgkmcnt(0)
	v_add_f32_e32 v13, v13, v30
	ds_bpermute_b32 v30, v8, v13
	global_store_dwordx2 v[4:5], v[16:17], off offset:1536
	s_waitcnt lgkmcnt(0)
	v_add_f32_e32 v13, v13, v30
	ds_bpermute_b32 v30, v9, v13
	s_waitcnt lgkmcnt(0)
	v_add_f32_e32 v13, v13, v30
	ds_bpermute_b32 v19, v10, v13
	s_waitcnt lgkmcnt(0)
	v_add_f32_e32 v13, v13, v19
	ds_bpermute_b32 v14, v11, v13
	v_cvt_pk_bf16_f32 v19, v24, v25
	global_store_dwordx2 v[4:5], v[18:19], off offset:1024
	s_and_saveexec_b64 s[18:19], vcc
	s_cbranch_execz .LBB0_820
	s_waitcnt lgkmcnt(0)
	v_add_f32_e32 v13, v13, v14
	v_mov_b64_e32 v[4:5], s[8:9]
	flat_store_dword v[4:5], v13
	s_branch .LBB0_820

; #define GAS __attribute__((address_space(1)))
; template <bool FIRST>
; __device__ __forceinline__ void norm_phase(const float* xp, const float* xs, float* out, unsigned char* ws, int mode, const float* gain, int gw, int NGW, int lane) {
;     ...
;     for (int m = gw; m < M; m += NGW) {
;         f32x4 v[4]; float s = 0.f;
;         if (FIRST) {
;             const float* src = (m < SEQ ? xp + (size_t)m * D : xs + (size_t)(m - SEQ) * D);
; #pragma unroll
;             for (int j = 0; j < 4; ++j) v[j] = *((const GAS f32x4*)src + lane + 64 * j);
;         } else {
; #pragma unroll
;             for (int j = 0; j < 4; ++j) { const u32x2 w = *((const GAS u32x2*)(xb + (size_t)m * D) + lane + 64 * j);
;                 v[j] = (f32x4){__uint_as_float(w.x << 16), __uint_as_float(w.x & 0xffff0000u), __uint_as_float(w.y << 16), __uint_as_float(w.y & 0xffff0000u)}; }
;         }
; #pragma unroll
;         for (int j = 0; j < 4; ++j) s += (v[j][0] * v[j][0] + v[j][1] * v[j][1]) + (v[j][2] * v[j][2] + v[j][3] * v[j][3]);
;         s = wave_sum(s);
;         if (!FIRST) {
;             const float rs = __builtin_amdgcn_rsqf(s * (1.0f / 1024.0f) + EPS); float s2 = 0.f;
; #pragma unroll
;             for (int j = 0; j < 4; ++j) { const f32x4 gg = *((const GAS f32x4*)gain + lane + 64 * j); v[j] = v[j] * rs * gg; s2 += (v[j][0] * v[j][0] + v[j][1] * v[j][1]) + (v[j][2] * v[j][2] + v[j][3] * v[j][3]); }
;             s = wave_sum(s2);
;         }
;         if (mode == 2) {
; #pragma unroll
;             for (int j = 0; j < 4; ++j) *((GAS f32x4*)(out + (size_t)m * D) + lane + 64 * j) = v[j];
.LBB0_1530:
	s_or_b64 exec, exec, s[34:35]
	s_and_b64 vcc, exec, s[6:7]
	s_waitcnt lgkmcnt(0)
	s_barrier
	s_cbranch_vccnz .LBB0_1533
	v_mbcnt_hi_u32_b32 v0, -1, v155
	v_and_b32_e32 v1, 64, v0
	v_add_u32_e32 v1, 64, v1
	v_xor_b32_e32 v2, 1, v0
	v_cmp_lt_i32_e32 vcc, v2, v1
	v_xor_b32_e32 v3, 2, v0
	v_xor_b32_e32 v4, 4, v0
	v_cndmask_b32_e32 v2, v0, v2, vcc
	v_cmp_lt_i32_e32 vcc, v3, v1
	v_xor_b32_e32 v5, 8, v0
	v_xor_b32_e32 v6, 16, v0
	v_cndmask_b32_e32 v3, v0, v3, vcc
	v_cmp_lt_i32_e32 vcc, v4, v1
	v_xor_b32_e32 v7, 32, v0
	v_ashrrev_i32_e32 v153, 31, v152
	v_cndmask_b32_e32 v4, v0, v4, vcc
	v_cmp_lt_i32_e32 vcc, v5, v1
	v_readlane_b32 s4, v234, 16
	s_mov_b64 s[0:1], 0xc4000
	v_cndmask_b32_e32 v5, v0, v5, vcc
	v_cmp_lt_i32_e32 vcc, v6, v1
	s_ashr_i32 s69, s68, 31
	v_readlane_b32 s14, v234, 26
	v_cndmask_b32_e32 v6, v0, v6, vcc
	v_cmp_lt_i32_e32 vcc, v7, v1
	v_readlane_b32 s15, v234, 27
	v_readlane_b32 s18, v234, 30
	v_cndmask_b32_e32 v0, v0, v7, vcc
	v_lshlrev_b32_e32 v7, 2, v0
	v_lshl_add_u64 v[0:1], v[152:153], 4, s[42:43]
	v_readlane_b32 s19, v234, 31
	v_lshl_add_u64 v[0:1], v[0:1], 0, s[0:1]
	s_lshl_b64 s[0:1], s[68:69], 12
	s_mov_b64 s[14:15], s[18:19]
	s_add_u32 s0, s14, s0
	v_readlane_b32 s5, v234, 17
	s_addc_u32 s1, s15, s1
	s_ashr_i32 s71, s70, 31
	s_lshl_b64 s[2:3], s[70:71], 12
	s_lshl_b64 s[4:5], s[68:69], 11
	s_add_u32 s4, s42, s4
	s_addc_u32 s5, s43, s5
	v_readlane_b32 s6, v234, 18
	v_readlane_b32 s7, v234, 19
	s_add_u32 s4, s4, 0x5400000
	v_lshlrev_b32_e32 v2, 2, v2
	v_lshlrev_b32_e32 v3, 2, v3
	v_lshlrev_b32_e32 v4, 2, v4
	v_lshlrev_b32_e32 v5, 2, v5
	v_lshlrev_b32_e32 v6, 2, v6
	s_addc_u32 s5, s5, 0
	s_lshl_b64 s[6:7], s[70:71], 11
	v_mov_b32_e32 v8, 0x358637bd
	v_readlane_b32 s8, v234, 20
	v_readlane_b32 s9, v234, 21
	v_readlane_b32 s10, v234, 22
	v_readlane_b32 s11, v234, 23
	v_readlane_b32 s12, v234, 24
	v_readlane_b32 s13, v234, 25
	v_readlane_b32 s16, v234, 28
	v_readlane_b32 s17, v234, 29
	global_load_dwordx4 v[60:63], v[0:1], off
	global_load_dwordx4 v[64:67], v[0:1], off offset:1024
	global_load_dwordx4 v[68:71], v[0:1], off offset:2048
	global_load_dwordx4 v[72:75], v[0:1], off offset:3072
	v_lshl_add_u64 v[84:85], v[152:153], 3, s[4:5]
	global_load_dwordx2 v[76:77], v[84:85], off offset:1536
	global_load_dwordx2 v[78:79], v[84:85], off
	global_load_dwordx2 v[80:81], v[84:85], off offset:512
	global_load_dwordx2 v[82:83], v[84:85], off offset:1024
	s_waitcnt vmcnt(0)
.LBB0_1532:
	s_add_i32 s68, s68, s70
	v_lshl_add_u64 v[26:27], v[152:153], 4, s[0:1]
	s_add_u32 s0, s0, s2
	s_addc_u32 s1, s1, s3
	s_add_u32 s4, s4, s6
	s_addc_u32 s5, s5, s7
	s_cmp_lt_i32 s68, 0xc000
	s_waitcnt vmcnt(4)
	v_mov_b64_e32 v[28:29], v[76:77]
	v_mov_b64_e32 v[30:31], v[78:79]
	v_mov_b64_e32 v[32:33], v[80:81]
	v_mov_b64_e32 v[34:35], v[82:83]
	s_cbranch_scc0 .Lnorm1_nopf
	v_lshl_add_u64 v[84:85], v[152:153], 3, s[4:5]
	global_load_dwordx2 v[76:77], v[84:85], off offset:1536
	global_load_dwordx2 v[78:79], v[84:85], off
	global_load_dwordx2 v[80:81], v[84:85], off offset:512
	global_load_dwordx2 v[82:83], v[84:85], off offset:1024
.Lnorm1_nopf:
	v_lshlrev_b32_e32 v37, 16, v28
	v_lshlrev_b32_e32 v40, 16, v30
	v_and_b32_e32 v41, 0xffff0000, v30
	v_lshlrev_b32_e32 v30, 16, v31
	v_and_b32_e32 v31, 0xffff0000, v31
	v_lshlrev_b32_e32 v43, 16, v33
	v_lshlrev_b32_e32 v42, 16, v32
	v_and_b32_e32 v33, 0xffff0000, v33
	v_and_b32_e32 v32, 0xffff0000, v32
	v_mul_f32_e32 v36, v31, v31
	v_pk_mul_f32 v[46:47], v[32:33], v[32:33]
	v_mul_f32_e32 v48, v41, v41
	v_mov_b32_e32 v49, v37
	v_lshlrev_b32_e32 v44, 16, v34
	v_and_b32_e32 v45, 0xffff0000, v34
	v_lshlrev_b32_e32 v34, 16, v35
	v_and_b32_e32 v35, 0xffff0000, v35
	v_mov_b32_e32 v54, v42
	v_mov_b32_e32 v55, v32
	v_mov_b32_e32 v32, v43
	v_pk_fma_f32 v[56:57], v[30:31], v[30:31], v[36:37] op_sel_hi:[1,1,0]
	v_pk_fma_f32 v[42:43], v[42:43], v[42:43], v[46:47]
	v_pk_fma_f32 v[46:47], v[40:41], v[40:41], v[48:49] op_sel_hi:[1,1,0]
	v_and_b32_e32 v39, 0xffff0000, v28
	v_lshlrev_b32_e32 v28, 16, v29
	v_and_b32_e32 v29, 0xffff0000, v29
	v_mul_f32_e32 v50, v45, v45
	v_mul_f32_e32 v52, v35, v35
	v_mov_b32_e32 v36, v46
	v_mov_b32_e32 v48, v56
	v_mul_f32_e32 v9, v39, v39
	v_mul_f32_e32 v58, v28, v28
	v_mul_f32_e32 v59, v29, v29
	v_mov_b32_e32 v38, v37
	v_pk_fma_f32 v[50:51], v[44:45], v[44:45], v[50:51] op_sel_hi:[1,1,0]
	v_pk_fma_f32 v[52:53], v[34:35], v[34:35], v[52:53] op_sel_hi:[1,1,0]
	v_pk_add_f32 v[46:47], v[46:47], v[56:57]
	v_pk_add_f32 v[42:43], v[42:43], v[42:43] op_sel:[0,1] op_sel_hi:[1,0]
	v_pk_mul_f32 v[36:37], v[36:37], v[48:49]
	v_mov_b32_e32 v51, v58
	v_mov_b32_e32 v53, v59
	v_mov_b32_e32 v43, v9
	v_mov_b32_e32 v47, v37
	v_pk_add_f32 v[48:49], v[50:51], v[52:53]
	v_pk_add_f32 v[36:37], v[46:47], v[42:43]
	s_nop 0
	v_pk_add_f32 v[36:37], v[36:37], v[48:49]
	s_nop 0
	v_add_f32_e32 v9, v36, v37
	ds_bpermute_b32 v36, v2, v9
	s_waitcnt lgkmcnt(0)
	v_add_f32_e32 v9, v9, v36
	ds_bpermute_b32 v36, v3, v9
	s_waitcnt lgkmcnt(0)
	v_add_f32_e32 v9, v9, v36
	ds_bpermute_b32 v36, v4, v9
	s_waitcnt lgkmcnt(0)
	v_add_f32_e32 v9, v9, v36
	ds_bpermute_b32 v36, v5, v9
	s_waitcnt lgkmcnt(0)
	v_add_f32_e32 v9, v9, v36
	ds_bpermute_b32 v36, v6, v9
	s_waitcnt lgkmcnt(0)
	v_add_f32_e32 v9, v9, v36
	ds_bpermute_b32 v36, v7, v9
	s_waitcnt lgkmcnt(0)
	v_add_f32_e32 v9, v9, v36
	v_fmamk_f32 v9, v9, 0x3a800000, v8
	v_rsq_f32_e32 v36, v9
	s_nop 0
	v_pk_mul_f32 v[40:41], v[36:37], v[40:41] op_sel_hi:[0,1]
	v_pk_mul_f32 v[30:31], v[36:37], v[30:31] op_sel_hi:[0,1]
	v_pk_mul_f32 v[42:43], v[36:37], v[54:55] op_sel_hi:[0,1]
	v_pk_mul_f32 v[32:33], v[36:37], v[32:33] op_sel_hi:[0,1]
	v_pk_mul_f32 v[44:45], v[36:37], v[44:45] op_sel_hi:[0,1]
	v_pk_mul_f32 v[34:35], v[36:37], v[34:35] op_sel_hi:[0,1]
	v_pk_mul_f32 v[38:39], v[38:39], v[36:37] op_sel_hi:[1,0]
	v_pk_mul_f32 v[28:29], v[28:29], v[36:37] op_sel_hi:[1,0]
	v_pk_mul_f32 v[12:13], v[62:63], v[30:31]
	v_pk_mul_f32 v[10:11], v[60:61], v[40:41]
	v_pk_mul_f32 v[16:17], v[66:67], v[32:33]
	v_pk_mul_f32 v[14:15], v[64:65], v[42:43]
	v_pk_mul_f32 v[20:21], v[70:71], v[34:35]
	v_pk_mul_f32 v[18:19], v[68:69], v[44:45]
	v_pk_mul_f32 v[24:25], v[74:75], v[28:29]
	v_pk_mul_f32 v[22:23], v[72:73], v[38:39]
	global_store_dwordx4 v[26:27], v[10:13], off
	global_store_dwordx4 v[26:27], v[14:17], off offset:1024
	global_store_dwordx4 v[26:27], v[18:21], off offset:2048
	global_store_dwordx4 v[26:27], v[22:25], off offset:3072
	s_cbranch_scc1 .LBB0_1532
